# v20 + mlaprep wave-wide sums via DPP row reductions and v_readlane broadcast instead of 12 ds_bpermute round trips
# speedup vs baseline: 1.0019x; 1.0019x over previous
; DI bft f2bf(float x) { unsigned u = __float_as_uint(x); u += 0x7fffu + ((u >> 16) & 1u); return (bft)(u >> 16); }
; DI float bf2f(bft h) { return __uint_as_float(((unsigned)h) << 16); }
; DI float wave_sum(float v) { for (int o = 32; o > 0; o >>= 1) v += __shfl_xor(v, o); return v; }
; DI void phase_mlaprep(const Params& p) {
;     ...
;   for (int it = blockIdx.x; it < T / 8; it += gridDim.x) {
;     int tok = it * 8 + wid; bft* r = lat + (size_t)tok * 704;
;     float q[6], kv[4], ss = 0, ss2 = 0;
;     for (int i = 0; i < 6; ++i) { q[i] = bf2f(r[lane + 64 * i]); ss += q[i] * q[i]; }
;     for (int i = 0; i < 4; ++i) { kv[i] = bf2f(r[384 + lane + 64 * i]); ss2 += kv[i] * kv[i]; }
;     float kr = bf2f(r[640 + lane]);
;     ss = wave_sum(ss); ss2 = wave_sum(ss2);
;     float rq = rsqrtf(ss * (1.f / 384) + EPS), rkv = rsqrtf(ss2 * (1.f / 256) + EPS);
;     for (int i = 0; i < 6; ++i) r[lane + 64 * i] = f2bf(q[i] * rq);
;     for (int i = 0; i < 4; ++i) r[384 + lane + 64 * i] = f2bf(kv[i] * rkv);
;     int pos = tok_pos(tok); float c = rt[pos * 64 + (lane & 31)], s = rt[pos * 64 + 32 + (lane & 31)];
;     float xo = __shfl_xor(kr, 32);
;     float o = lane < 32 ? kr * c - xo * s : xo * s + kr * c;
;     r[640 + lane] = f2bf(o);
;   }
.LBB0_315:
	v_mad_i64_i32 v[4:5], s[8:9], v11, s4, v[0:1]
	global_load_ushort v16, v[4:5], off offset:384
	global_load_ushort v18, v[4:5], off offset:256
	global_load_ushort v19, v[4:5], off offset:640
	global_load_ushort v20, v[4:5], off offset:512
	global_load_ushort v21, v[4:5], off offset:896
	global_load_ushort v22, v[4:5], off offset:768
	global_load_ushort v23, v[4:5], off offset:1152
	global_load_ushort v24, v[4:5], off offset:1024
	global_load_ushort v25, v[4:5], off offset:128
	global_load_ushort v26, v[4:5], off
	global_load_ushort v27, v[4:5], off offset:1280
	v_cmp_gt_i32_e64 s[8:9], s13, v11
	s_add_i32 s14, s14, s28
	s_cmpk_lt_i32 s14, 0x1800
	v_cndmask_b32_e64 v15, v12, v13, s[8:9]
	v_and_b32_e32 v15, v15, v11
	v_lshl_or_b32 v15, v15, 8, v14
	global_load_dword v38, v15, s[0:1] offset:128
	global_load_dword v39, v15, s[0:1]
	v_add_u32_e32 v11, s3, v11
	s_waitcnt vmcnt(12)
	v_lshlrev_b32_e32 v17, 16, v16
	s_waitcnt vmcnt(11)
	v_lshlrev_b32_e32 v16, 16, v18
	s_waitcnt vmcnt(10)
	v_lshlrev_b32_e32 v19, 16, v19
	s_waitcnt vmcnt(9)
	v_lshlrev_b32_e32 v18, 16, v20
	s_waitcnt vmcnt(8)
	v_lshlrev_b32_e32 v21, 16, v21
	s_waitcnt vmcnt(7)
	v_lshlrev_b32_e32 v20, 16, v22
	s_waitcnt vmcnt(6)
	v_lshlrev_b32_e32 v23, 16, v23
	s_waitcnt vmcnt(5)
	v_lshlrev_b32_e32 v22, 16, v24
	s_waitcnt vmcnt(4)
	v_lshlrev_b32_e32 v25, 16, v25
	s_waitcnt vmcnt(3)
	v_lshlrev_b32_e32 v24, 16, v26
	s_waitcnt vmcnt(2)
	v_lshlrev_b32_e32 v15, 16, v27
	v_pk_mul_f32 v[26:27], v[16:17], v[16:17]
	v_pk_mul_f32 v[28:29], v[18:19], v[18:19]
	v_mul_f32_e32 v26, v25, v25
	v_pk_mul_f32 v[32:33], v[22:23], v[22:23]
	v_pk_fma_f32 v[34:35], v[24:25], v[24:25], v[26:27] op_sel_hi:[1,1,0]
	v_pk_mul_f32 v[30:31], v[20:21], v[20:21]
	v_mov_b32_e32 v36, v32
	v_mov_b32_e32 v37, v28
	v_mov_b32_e32 v28, v33
	v_pk_fma_f32 v[32:33], v[16:17], v[16:17], v[34:35]
	v_mov_b32_e32 v26, v31
	v_mov_b32_e32 v31, v32
	v_pk_add_f32 v[26:27], v[30:31], v[26:27]
	ds_bpermute_b32 v40, v3, v15
	v_pk_add_f32 v[26:27], v[26:27], v[36:37]
	s_waitcnt vmcnt(1) lgkmcnt(0)
	v_mul_f32_e32 v30, v38, v40
	v_pk_add_f32 v[26:27], v[26:27], v[28:29]
	v_cndmask_b32_e64 v30, v30, -v30, vcc
	s_waitcnt vmcnt(0)
	v_fmac_f32_e32 v30, v39, v15
	v_bfe_u32 v15, v30, 16, 1
	v_add3_u32 v15, v30, v15, s12
	global_store_short_d16_hi v[4:5], v15, off offset:1280
	v_add_f32_dpp v26, v26, v26 quad_perm:[1,0,3,2] row_mask:0xf bank_mask:0xf
	v_add_f32_dpp v27, v27, v27 quad_perm:[1,0,3,2] row_mask:0xf bank_mask:0xf
	s_nop 1
	v_add_f32_dpp v26, v26, v26 quad_perm:[2,3,0,1] row_mask:0xf bank_mask:0xf
	v_add_f32_dpp v27, v27, v27 quad_perm:[2,3,0,1] row_mask:0xf bank_mask:0xf
	s_nop 1
	v_add_f32_dpp v26, v26, v26 row_half_mirror row_mask:0xf bank_mask:0xf
	v_add_f32_dpp v27, v27, v27 row_half_mirror row_mask:0xf bank_mask:0xf
	s_nop 1
	v_add_f32_dpp v26, v26, v26 row_mirror row_mask:0xf bank_mask:0xf
	v_add_f32_dpp v27, v27, v27 row_mirror row_mask:0xf bank_mask:0xf
	s_nop 1
	v_add_f32_dpp v26, v26, v26 row_bcast:15 row_mask:0xa bank_mask:0xf
	v_add_f32_dpp v27, v27, v27 row_bcast:15 row_mask:0xa bank_mask:0xf
	s_nop 1
	v_add_f32_dpp v26, v26, v26 row_bcast:31 row_mask:0xc bank_mask:0xf
	v_add_f32_dpp v27, v27, v27 row_bcast:31 row_mask:0xc bank_mask:0xf
	s_nop 1
	v_readlane_b32 s8, v26, 63
	v_readlane_b32 s9, v27, 63
	s_nop 3
	v_mov_b32_e32 v26, s8
	v_mov_b32_e32 v27, s9
	s_nop 0
	v_pk_fma_f32 v[26:27], v[26:27], s[6:7], v[2:3] op_sel_hi:[1,1,0]
	s_nop 0
	v_mul_f32_e32 v15, 0x4b800000, v27
	v_cmp_gt_f32_e64 s[10:11], s5, v27
	v_mul_f32_e32 v28, 0x4b800000, v26
	v_cmp_gt_f32_e64 s[8:9], s5, v26
	v_cndmask_b32_e64 v15, v27, v15, s[10:11]
	v_rsq_f32_e32 v15, v15
	v_cndmask_b32_e64 v26, v26, v28, s[8:9]
	v_rsq_f32_e32 v26, v26
	v_mul_f32_e32 v27, 0x45800000, v15
	v_cndmask_b32_e64 v15, v15, v27, s[10:11]
	v_mul_f32_e32 v28, 0x45800000, v26
	v_cndmask_b32_e64 v26, v26, v28, s[8:9]
	v_mul_f32_e32 v24, v15, v24
	v_mul_f32_e32 v25, v15, v25
	v_mul_f32_e32 v16, v15, v16
	v_mul_f32_e32 v17, v15, v17
	v_mul_f32_e32 v18, v15, v18
	v_mul_f32_e32 v15, v15, v19
	v_mul_f32_e32 v19, v26, v20
	v_mul_f32_e32 v20, v26, v21
	v_mul_f32_e32 v21, v26, v22
	v_mul_f32_e32 v22, v26, v23
	v_bfe_u32 v23, v24, 16, 1
	v_bfe_u32 v26, v25, 16, 1
	v_bfe_u32 v27, v16, 16, 1
	v_bfe_u32 v28, v17, 16, 1
	v_bfe_u32 v29, v18, 16, 1
	v_bfe_u32 v30, v15, 16, 1
	v_bfe_u32 v31, v19, 16, 1
	v_bfe_u32 v32, v20, 16, 1
	v_bfe_u32 v33, v21, 16, 1
	v_bfe_u32 v34, v22, 16, 1
	v_add3_u32 v23, v24, v23, s12
	v_add3_u32 v24, v25, v26, s12
	v_add3_u32 v16, v16, v27, s12
	v_add3_u32 v17, v17, v28, s12
	v_add3_u32 v18, v18, v29, s12
	v_add3_u32 v15, v15, v30, s12
	v_add3_u32 v19, v19, v31, s12
	v_add3_u32 v20, v20, v32, s12
	v_add3_u32 v21, v21, v33, s12
	v_add3_u32 v22, v22, v34, s12
	global_store_short_d16_hi v[4:5], v23, off
	global_store_short_d16_hi v[4:5], v24, off offset:128
	global_store_short_d16_hi v[4:5], v16, off offset:256
	global_store_short_d16_hi v[4:5], v17, off offset:384
	global_store_short_d16_hi v[4:5], v18, off offset:512
	global_store_short_d16_hi v[4:5], v15, off offset:640
	global_store_short_d16_hi v[4:5], v19, off offset:768
	global_store_short_d16_hi v[4:5], v20, off offset:896
	global_store_short_d16_hi v[4:5], v21, off offset:1024
	global_store_short_d16_hi v[4:5], v22, off offset:1152
	s_cbranch_scc1 .LBB0_315
